# s27 with four early writebacks per XCD per barrier (every 8th arriving workgroup)
# speedup vs baseline: 1.0000x; 1.0000x over previous
; __device__ __forceinline__ unsigned xb_ld(unsigned* p)              { return __hip_atomic_load(p, __ATOMIC_RELAXED, __HIP_MEMORY_SCOPE_AGENT); }
; __device__ __forceinline__ unsigned xb_add(unsigned* p, unsigned v) { return __hip_atomic_fetch_add(p, v, __ATOMIC_RELAXED, __HIP_MEMORY_SCOPE_AGENT); }
; #define XB_SPIN(cond, bar) do { unsigned _sp = 0; while (cond) { __builtin_amdgcn_s_sleep(1); \
;     if ((++_sp & 255u) == 0u) { if (xb_ld(&(bar)[XB_TMO])) break; if (_sp > XB_SPIN_CAP) { atomicAdd(&(bar)[XB_TMO], 1u); break; } } } } while (0)
; __device__ __forceinline__ void xcd_barrier(const XcdBarrier& b, const bool t0) {
;     ...
;         const unsigned old = xb_add(&bar[XB_XSUB(b.x)], 1u);
;         const unsigned gen = old / nloc;
;         if (old + 1u == (gen + 1u) * nloc) {
;             __builtin_amdgcn_fence(__ATOMIC_RELEASE, "agent");
;             asm volatile("s_waitcnt vmcnt(0)" ::: "memory");
;             const unsigned og = xb_add(&bar[XB_TOP], 1u);
;             const unsigned tg = og / nx;
;             if (og + 1u == (tg + 1u) * nx) xb_add(&bar[XB_TOPGEN], 1u);
;             else XB_SPIN(xb_ld(&bar[XB_TOPGEN]) == tg, bar);
;             __builtin_amdgcn_fence(__ATOMIC_ACQUIRE, "agent");
;             xb_add(&bar[XB_XGEN(b.x)], 1u);
;             asm volatile("s_waitcnt vmcnt(0)" ::: "memory");
;         } else {
;             XB_SPIN(xb_ld(&bar[XB_XGEN(b.x)]) == gen, bar);
.LBB0_56:
	s_or_b64 exec, exec, s[12:13]
	v_cvt_f32_u32_e32 v4, v2
	s_waitcnt vmcnt(0)
	v_readfirstlane_b32 s0, v3
	v_sub_u32_e32 v3, 0, v2
	v_rcp_iflag_f32_e32 v4, v4
	v_add_u32_e32 v5, s0, v1
	v_mul_f32_e32 v4, 0x4f7ffffe, v4
	v_cvt_u32_f32_e32 v4, v4
	v_mul_lo_u32 v1, v3, v4
	v_mul_hi_u32 v1, v4, v1
	v_add_u32_e32 v1, v4, v1
	v_mul_hi_u32 v1, v5, v1
	v_mul_lo_u32 v3, v1, v2
	v_sub_u32_e32 v3, v5, v3
	v_add_u32_e32 v4, 1, v1
	v_cmp_ge_u32_e32 vcc, v3, v2
	s_nop 1
	v_cndmask_b32_e32 v1, v1, v4, vcc
	v_sub_u32_e32 v4, v3, v2
	v_cndmask_b32_e32 v3, v3, v4, vcc
	v_add_u32_e32 v4, 1, v1
	v_cmp_ge_u32_e32 vcc, v3, v2
	v_add_u32_e32 v3, 1, v5
	s_nop 0
	v_cndmask_b32_e32 v1, v1, v4, vcc
	v_mul_lo_u32 v4, v2, v1
	v_add_u32_e32 v2, v4, v2
	v_cmp_ne_u32_e32 vcc, v3, v2
	s_and_saveexec_b64 s[0:1], vcc
	s_xor_b64 s[10:11], exec, s[0:1]
	s_cbranch_execz .LBB0_70
	v_sub_u32_e32 v0, v2, v3
	v_and_b32_e32 v0, 7, v0
	v_cmp_eq_u32_e32 vcc, 7, v0
	s_and_saveexec_b64 s[16:17], vcc
	s_cbranch_execz .Lfwb_8
	buffer_wbl2 sc1

; __device__ __forceinline__ unsigned xb_ld(unsigned* p)              { return __hip_atomic_load(p, __ATOMIC_RELAXED, __HIP_MEMORY_SCOPE_AGENT); }
; __device__ __forceinline__ unsigned xb_add(unsigned* p, unsigned v) { return __hip_atomic_fetch_add(p, v, __ATOMIC_RELAXED, __HIP_MEMORY_SCOPE_AGENT); }
; #define XB_SPIN(cond, bar) do { unsigned _sp = 0; while (cond) { __builtin_amdgcn_s_sleep(1); \
;     if ((++_sp & 255u) == 0u) { if (xb_ld(&(bar)[XB_TMO])) break; if (_sp > XB_SPIN_CAP) { atomicAdd(&(bar)[XB_TMO], 1u); break; } } } } while (0)
; __device__ __forceinline__ void xcd_barrier(const XcdBarrier& b, const bool t0) {
;     ...
;         const unsigned old = xb_add(&bar[XB_XSUB(b.x)], 1u);
;         const unsigned gen = old / nloc;
;         if (old + 1u == (gen + 1u) * nloc) {
;             __builtin_amdgcn_fence(__ATOMIC_RELEASE, "agent");
;             asm volatile("s_waitcnt vmcnt(0)" ::: "memory");
;             const unsigned og = xb_add(&bar[XB_TOP], 1u);
;             const unsigned tg = og / nx;
;             if (og + 1u == (tg + 1u) * nx) xb_add(&bar[XB_TOPGEN], 1u);
;             else XB_SPIN(xb_ld(&bar[XB_TOPGEN]) == tg, bar);
;             __builtin_amdgcn_fence(__ATOMIC_ACQUIRE, "agent");
;             xb_add(&bar[XB_XGEN(b.x)], 1u);
;             asm volatile("s_waitcnt vmcnt(0)" ::: "memory");
;         } else {
;             XB_SPIN(xb_ld(&bar[XB_XGEN(b.x)]) == gen, bar);
.LBB0_478:
	s_or_b64 exec, exec, s[12:13]
	v_cvt_f32_u32_e32 v4, v2
	s_waitcnt vmcnt(0)
	v_readfirstlane_b32 s0, v3
	v_sub_u32_e32 v3, 0, v2
	v_rcp_iflag_f32_e32 v4, v4
	v_add_u32_e32 v5, s0, v1
	v_mul_f32_e32 v4, 0x4f7ffffe, v4
	v_cvt_u32_f32_e32 v4, v4
	v_mul_lo_u32 v1, v3, v4
	v_mul_hi_u32 v1, v4, v1
	v_add_u32_e32 v1, v4, v1
	v_mul_hi_u32 v1, v5, v1
	v_mul_lo_u32 v3, v1, v2
	v_sub_u32_e32 v3, v5, v3
	v_add_u32_e32 v4, 1, v1
	v_cmp_ge_u32_e32 vcc, v3, v2
	s_nop 1
	v_cndmask_b32_e32 v1, v1, v4, vcc
	v_sub_u32_e32 v4, v3, v2
	v_cndmask_b32_e32 v3, v3, v4, vcc
	v_add_u32_e32 v4, 1, v1
	v_cmp_ge_u32_e32 vcc, v3, v2
	v_add_u32_e32 v3, 1, v5
	s_nop 0
	v_cndmask_b32_e32 v1, v1, v4, vcc
	v_mul_lo_u32 v4, v2, v1
	v_add_u32_e32 v2, v4, v2
	v_cmp_ne_u32_e32 vcc, v3, v2
	s_and_saveexec_b64 s[0:1], vcc
	s_xor_b64 s[10:11], exec, s[0:1]
	s_cbranch_execz .LBB0_492
	v_sub_u32_e32 v0, v2, v3
	v_and_b32_e32 v0, 7, v0
	v_cmp_eq_u32_e32 vcc, 7, v0
	s_and_saveexec_b64 s[22:23], vcc
	s_cbranch_execz .Lfwb_5
	buffer_wbl2 sc1

; __device__ __forceinline__ unsigned xb_ld(unsigned* p)              { return __hip_atomic_load(p, __ATOMIC_RELAXED, __HIP_MEMORY_SCOPE_AGENT); }
; __device__ __forceinline__ unsigned xb_add(unsigned* p, unsigned v) { return __hip_atomic_fetch_add(p, v, __ATOMIC_RELAXED, __HIP_MEMORY_SCOPE_AGENT); }
; #define XB_SPIN(cond, bar) do { unsigned _sp = 0; while (cond) { __builtin_amdgcn_s_sleep(1); \
;     if ((++_sp & 255u) == 0u) { if (xb_ld(&(bar)[XB_TMO])) break; if (_sp > XB_SPIN_CAP) { atomicAdd(&(bar)[XB_TMO], 1u); break; } } } } while (0)
; __device__ __forceinline__ void xcd_barrier(const XcdBarrier& b, const bool t0) {
;     ...
;         const unsigned old = xb_add(&bar[XB_XSUB(b.x)], 1u);
;         const unsigned gen = old / nloc;
;         if (old + 1u == (gen + 1u) * nloc) {
;             __builtin_amdgcn_fence(__ATOMIC_RELEASE, "agent");
;             asm volatile("s_waitcnt vmcnt(0)" ::: "memory");
;             const unsigned og = xb_add(&bar[XB_TOP], 1u);
;             const unsigned tg = og / nx;
;             if (og + 1u == (tg + 1u) * nx) xb_add(&bar[XB_TOPGEN], 1u);
;             else XB_SPIN(xb_ld(&bar[XB_TOPGEN]) == tg, bar);
;             __builtin_amdgcn_fence(__ATOMIC_ACQUIRE, "agent");
;             xb_add(&bar[XB_XGEN(b.x)], 1u);
;             asm volatile("s_waitcnt vmcnt(0)" ::: "memory");
;         } else {
;             XB_SPIN(xb_ld(&bar[XB_XGEN(b.x)]) == gen, bar);
.LBB0_558:
	s_or_b64 exec, exec, s[12:13]
	v_cvt_f32_u32_e32 v4, v2
	s_waitcnt vmcnt(0)
	v_readfirstlane_b32 s0, v3
	v_sub_u32_e32 v3, 0, v2
	v_rcp_iflag_f32_e32 v4, v4
	v_add_u32_e32 v5, s0, v1
	v_mul_f32_e32 v4, 0x4f7ffffe, v4
	v_cvt_u32_f32_e32 v4, v4
	v_mul_lo_u32 v1, v3, v4
	v_mul_hi_u32 v1, v4, v1
	v_add_u32_e32 v1, v4, v1
	v_mul_hi_u32 v1, v5, v1
	v_mul_lo_u32 v3, v1, v2
	v_sub_u32_e32 v3, v5, v3
	v_add_u32_e32 v4, 1, v1
	v_cmp_ge_u32_e32 vcc, v3, v2
	s_nop 1
	v_cndmask_b32_e32 v1, v1, v4, vcc
	v_sub_u32_e32 v4, v3, v2
	v_cndmask_b32_e32 v3, v3, v4, vcc
	v_add_u32_e32 v4, 1, v1
	v_cmp_ge_u32_e32 vcc, v3, v2
	v_add_u32_e32 v3, 1, v5
	s_nop 0
	v_cndmask_b32_e32 v1, v1, v4, vcc
	v_mul_lo_u32 v4, v2, v1
	v_add_u32_e32 v2, v4, v2
	v_cmp_ne_u32_e32 vcc, v3, v2
	s_and_saveexec_b64 s[0:1], vcc
	s_xor_b64 s[10:11], exec, s[0:1]
	s_cbranch_execz .LBB0_572
	v_sub_u32_e32 v0, v2, v3
	v_and_b32_e32 v0, 7, v0
	v_cmp_eq_u32_e32 vcc, 7, v0
	s_and_saveexec_b64 s[20:21], vcc
	s_cbranch_execz .Lfwb_4
	buffer_wbl2 sc1

; __device__ __forceinline__ unsigned xb_ld(unsigned* p)              { return __hip_atomic_load(p, __ATOMIC_RELAXED, __HIP_MEMORY_SCOPE_AGENT); }
; __device__ __forceinline__ unsigned xb_add(unsigned* p, unsigned v) { return __hip_atomic_fetch_add(p, v, __ATOMIC_RELAXED, __HIP_MEMORY_SCOPE_AGENT); }
; #define XB_SPIN(cond, bar) do { unsigned _sp = 0; while (cond) { __builtin_amdgcn_s_sleep(1); \
;     if ((++_sp & 255u) == 0u) { if (xb_ld(&(bar)[XB_TMO])) break; if (_sp > XB_SPIN_CAP) { atomicAdd(&(bar)[XB_TMO], 1u); break; } } } } while (0)
; __device__ __forceinline__ void xcd_barrier(const XcdBarrier& b, const bool t0) {
;     ...
;         const unsigned old = xb_add(&bar[XB_XSUB(b.x)], 1u);
;         const unsigned gen = old / nloc;
;         if (old + 1u == (gen + 1u) * nloc) {
;             __builtin_amdgcn_fence(__ATOMIC_RELEASE, "agent");
;             asm volatile("s_waitcnt vmcnt(0)" ::: "memory");
;             const unsigned og = xb_add(&bar[XB_TOP], 1u);
;             const unsigned tg = og / nx;
;             if (og + 1u == (tg + 1u) * nx) xb_add(&bar[XB_TOPGEN], 1u);
;             else XB_SPIN(xb_ld(&bar[XB_TOPGEN]) == tg, bar);
;             __builtin_amdgcn_fence(__ATOMIC_ACQUIRE, "agent");
;             xb_add(&bar[XB_XGEN(b.x)], 1u);
;             asm volatile("s_waitcnt vmcnt(0)" ::: "memory");
;         } else {
;             XB_SPIN(xb_ld(&bar[XB_XGEN(b.x)]) == gen, bar);
.LBB0_641:
	s_or_b64 exec, exec, s[12:13]
	v_cvt_f32_u32_e32 v4, v2
	s_waitcnt vmcnt(0)
	v_readfirstlane_b32 s0, v3
	v_sub_u32_e32 v3, 0, v2
	v_rcp_iflag_f32_e32 v4, v4
	v_add_u32_e32 v5, s0, v1
	v_mul_f32_e32 v4, 0x4f7ffffe, v4
	v_cvt_u32_f32_e32 v4, v4
	v_mul_lo_u32 v1, v3, v4
	v_mul_hi_u32 v1, v4, v1
	v_add_u32_e32 v1, v4, v1
	v_mul_hi_u32 v1, v5, v1
	v_mul_lo_u32 v3, v1, v2
	v_sub_u32_e32 v3, v5, v3
	v_add_u32_e32 v4, 1, v1
	v_cmp_ge_u32_e32 vcc, v3, v2
	s_nop 1
	v_cndmask_b32_e32 v1, v1, v4, vcc
	v_sub_u32_e32 v4, v3, v2
	v_cndmask_b32_e32 v3, v3, v4, vcc
	v_add_u32_e32 v4, 1, v1
	v_cmp_ge_u32_e32 vcc, v3, v2
	v_add_u32_e32 v3, 1, v5
	s_nop 0
	v_cndmask_b32_e32 v1, v1, v4, vcc
	v_mul_lo_u32 v4, v2, v1
	v_add_u32_e32 v2, v4, v2
	v_cmp_ne_u32_e32 vcc, v3, v2
	s_and_saveexec_b64 s[0:1], vcc
	s_xor_b64 s[10:11], exec, s[0:1]
	s_cbranch_execz .LBB0_655
	v_sub_u32_e32 v0, v2, v3
	v_and_b32_e32 v0, 7, v0
	v_cmp_eq_u32_e32 vcc, 7, v0
	s_and_saveexec_b64 s[18:19], vcc
	s_cbranch_execz .Lfwb_3
	buffer_wbl2 sc1
